# aprep q/k rope: both rope cos/sin load pairs issued together (one memory round trip instead of two per task batch)
# baseline (speedup 1.0000x reference)
.LBB0_623:
	s_or_b64 exec, exec, s[0:1]
	s_waitcnt lgkmcnt(0)
	s_barrier
	ds_read_b32 v0, v1 offset:208
	s_movk_i32 s0, 0x54f
	s_waitcnt lgkmcnt(0)
	v_cmp_lt_i32_e32 vcc, s0, v0
	s_mov_b64 s[0:1], -1
	s_cbranch_vccnz .LBB0_620
	v_mov_b32_e32 v2, v201
	s_mov_b32 s0, 0xd000
	v_ashrrev_i32_e32 v2, 8, v2
	v_mad_i32_i24 v174, v2, s0, v207
	v_lshl_add_u32 v0, v0, 1, v2
	s_movk_i32 s0, 0x87f
	v_cmp_lt_i32_e32 vcc, s0, v0
	s_and_saveexec_b64 s[0:1], vcc
	s_xor_b64 s[44:45], exec, s[0:1]
	s_cbranch_execz .LBB0_709
	v_add_u32_e32 v0, 0xfffff780, v0
	s_mov_b32 s0, 0xf0f0f0f1
	v_mul_hi_u32 v2, v0, s0
	v_lshrrev_b32_e32 v32, 6, v2
	s_movk_i32 s0, 0x44
	v_mul_lo_u32 v2, v32, s0
	v_sub_u32_e32 v33, v0, v2
	s_movk_i32 s0, 0x1100
	v_mul_lo_u32 v35, v32, s0
	v_lshlrev_b32_e32 v34, 6, v33
	v_mov_b32_e32 v37, v201
	v_add_u32_e32 v36, v35, v34
	v_mov_b64_e32 v[2:3], s[20:21]
	v_bfe_u32 v41, v37, 2, 6
	v_lshlrev_b32_sdwa v38, v198, v37 dst_sel:DWORD dst_unused:UNUSED_PAD src0_sel:DWORD src1_sel:BYTE_0
	v_and_b32_e32 v8, 24, v38
	v_or_b32_e32 v0, v41, v36
	v_mad_u64_u32 v[4:5], s[0:1], v0, s83, v[2:3]
	v_lshlrev_b32_e32 v2, 1, v8
	v_mov_b32_e32 v3, v1
	v_lshl_add_u64 v[6:7], v[4:5], 0, v[2:3]
	global_load_dwordx4 v[12:15], v[6:7], off offset:1568
	global_load_dwordx4 v[16:19], v[6:7], off offset:1632
	v_mov_b32_e32 v5, v1
	v_lshlrev_b32_e32 v4, 2, v8
	v_lshl_add_u64 v[10:11], s[22:23], 0, v[4:5]
	global_load_dwordx4 v[20:23], v[10:11], off
	global_load_dwordx4 v[24:27], v[10:11], off offset:128
	global_load_dwordx4 v[28:31], v[10:11], off offset:16
	global_load_dwordx4 v[42:45], v[10:11], off offset:144
	v_and_b32_e32 v9, 64, v208
	v_xor_b32_e32 v8, 1, v208
	v_add_u32_e32 v40, 64, v9
	v_cmp_lt_i32_e32 vcc, v8, v40
	v_or_b32_e32 v60, v41, v34
	v_cmp_gt_u32_e64 s[0:1], 4, v33
	v_cndmask_b32_e32 v8, v208, v8, vcc
	v_lshlrev_b32_e32 v39, 2, v8
	v_cmp_lt_u32_e64 s[2:3], 3, v33
	s_waitcnt vmcnt(0) lgkmcnt(0)
	v_lshlrev_b32_e32 v8, 16, v12
	v_lshlrev_b32_e32 v48, 16, v16
	v_and_b32_e32 v49, 0xffff0000, v16
	v_and_b32_e32 v9, 0xffff0000, v12
	v_lshlrev_b32_e32 v16, 16, v17
	v_and_b32_e32 v17, 0xffff0000, v17
	v_pk_mul_f32 v[56:57], v[48:49], v[48:49]
	v_lshlrev_b32_e32 v12, 16, v13
	v_and_b32_e32 v13, 0xffff0000, v13
	v_pk_mul_f32 v[54:55], v[16:17], v[16:17]
	v_pk_fma_f32 v[56:57], v[8:9], v[8:9], v[56:57]
	v_lshlrev_b32_e32 v50, 16, v18
	v_and_b32_e32 v51, 0xffff0000, v18
	v_pk_fma_f32 v[54:55], v[12:13], v[12:13], v[54:55]
	v_add_f32_e32 v56, v56, v57
	v_lshlrev_b32_e32 v46, 16, v14
	v_and_b32_e32 v47, 0xffff0000, v14
	v_pk_mul_f32 v[52:53], v[50:51], v[50:51]
	v_add_f32_e32 v54, v56, v54
	v_lshlrev_b32_e32 v18, 16, v19
	v_and_b32_e32 v19, 0xffff0000, v19
	v_pk_fma_f32 v[52:53], v[46:47], v[46:47], v[52:53]
	v_add_f32_e32 v54, v55, v54
	v_lshlrev_b32_e32 v14, 16, v15
	v_and_b32_e32 v15, 0xffff0000, v15
	v_pk_mul_f32 v[58:59], v[18:19], v[18:19]
	v_add_f32_e32 v52, v52, v54
	v_pk_fma_f32 v[58:59], v[14:15], v[14:15], v[58:59]
	v_add_f32_e32 v52, v53, v52
	v_add_f32_e32 v52, v58, v52
	v_add_f32_e32 v52, v59, v52
	ds_bpermute_b32 v53, v39, v52
	v_xor_b32_e32 v54, 2, v208
	v_cmp_lt_i32_e32 vcc, v54, v40
	s_waitcnt lgkmcnt(0)
	v_add_f32_e32 v52, v52, v53
	v_cndmask_b32_e32 v40, v208, v54, vcc
	v_lshlrev_b32_e32 v40, 2, v40
	ds_bpermute_b32 v53, v40, v52
	s_waitcnt lgkmcnt(0)
	v_add_f32_e32 v52, v52, v53
	v_fmamk_f32 v52, v52, 0x3c800000, v206
	v_mul_f32_e32 v53, 0x4b800000, v52
	v_cmp_gt_f32_e32 vcc, s35, v52
	s_nop 1
	v_cndmask_b32_e32 v52, v52, v53, vcc
	v_rsq_f32_e32 v52, v52
	s_nop 0
	v_mul_f32_e32 v53, 0x45800000, v52
	v_cndmask_b32_e32 v52, v52, v53, vcc
	v_pk_mul_f32 v[8:9], v[52:53], v[8:9] op_sel_hi:[0,1]
	v_pk_mul_f32 v[48:49], v[52:53], v[48:49] op_sel_hi:[0,1]
	v_pk_mul_f32 v[54:55], v[52:53], v[12:13] op_sel_hi:[0,1]
	v_pk_mul_f32 v[56:57], v[52:53], v[16:17] op_sel_hi:[0,1]
	v_pk_mul_f32 v[46:47], v[52:53], v[46:47] op_sel_hi:[0,1]
	v_pk_mul_f32 v[50:51], v[52:53], v[50:51] op_sel_hi:[0,1]
	v_pk_mul_f32 v[58:59], v[52:53], v[14:15] op_sel_hi:[0,1]
	v_pk_mul_f32 v[52:53], v[52:53], v[18:19] op_sel_hi:[0,1]
	v_pk_mul_f32 v[16:17], v[20:21], v[8:9]
	v_pk_mul_f32 v[12:13], v[24:25], v[48:49]
	v_pk_mul_f32 v[20:21], v[22:23], v[54:55]
	v_pk_mul_f32 v[14:15], v[26:27], v[56:57]
	v_pk_mul_f32 v[24:25], v[28:29], v[46:47]
	v_pk_mul_f32 v[18:19], v[42:43], v[50:51]
	v_pk_mul_f32 v[26:27], v[30:31], v[58:59]
	v_pk_mul_f32 v[22:23], v[44:45], v[52:53]
	v_lshlrev_b32_e32 v8, 5, v60
	s_and_saveexec_b64 s[4:5], s[2:3]
	s_cbranch_execz .LBB0_627
	v_mov_b32_e32 v9, v1
	v_lshl_add_u64 v[28:29], v[8:9], 2, s[64:65]
	v_lshl_add_u64 v[30:31], s[24:25], 0, v[28:29]
	v_lshl_add_u64 v[46:47], v[30:31], 0, v[4:5]
	v_lshl_add_u64 v[28:29], s[26:27], 0, v[28:29]
	v_lshl_add_u64 v[48:49], v[28:29], 0, v[4:5]
	global_load_dwordx4 v[28:31], v[46:47], off
	global_load_dwordx4 v[42:45], v[48:49], off
	global_load_dwordx4 v[212:215], v[46:47], off offset:16
	global_load_dwordx4 v[216:219], v[48:49], off offset:16
	s_waitcnt vmcnt(0) lgkmcnt(0)
	v_pk_mul_f32 v[50:51], v[16:17], v[42:43]
	v_pk_mul_f32 v[42:43], v[12:13], v[42:43]
	v_pk_fma_f32 v[12:13], v[12:13], v[28:29], v[50:51]
	v_pk_fma_f32 v[16:17], v[16:17], v[28:29], v[42:43] neg_lo:[0,0,1] neg_hi:[0,0,1]
	v_pk_mul_f32 v[28:29], v[20:21], v[44:45]
	v_pk_mul_f32 v[42:43], v[14:15], v[44:45]
	v_pk_fma_f32 v[14:15], v[14:15], v[30:31], v[28:29]
	v_pk_fma_f32 v[20:21], v[20:21], v[30:31], v[42:43] neg_lo:[0,0,1] neg_hi:[0,0,1]
	v_pk_mul_f32 v[46:47], v[24:25], v[216:217]
	v_pk_mul_f32 v[216:217], v[18:19], v[216:217]
	v_pk_fma_f32 v[18:19], v[18:19], v[212:213], v[46:47]
	v_pk_fma_f32 v[24:25], v[24:25], v[212:213], v[216:217] neg_lo:[0,0,1] neg_hi:[0,0,1]
	v_pk_mul_f32 v[212:213], v[26:27], v[218:219]
	v_pk_mul_f32 v[216:217], v[22:23], v[218:219]
	v_pk_fma_f32 v[22:23], v[22:23], v[214:215], v[212:213]
	v_pk_fma_f32 v[26:27], v[26:27], v[214:215], v[216:217] neg_lo:[0,0,1] neg_hi:[0,0,1]
.LBB0_627:
	s_or_b64 exec, exec, s[4:5]
	global_load_dwordx4 v[28:31], v[6:7], off offset:1696
	global_load_dwordx4 v[42:45], v[6:7], off offset:1760
	v_pk_mul_f32 v[46:47], v[12:13], s[66:67] op_sel_hi:[1,0]
	v_lshlrev_b64 v[12:13], 9, v[0:1]
	v_pk_mul_f32 v[26:27], v[26:27], s[66:67] op_sel_hi:[1,0]
	v_pk_mul_f32 v[24:25], v[24:25], s[66:67] op_sel_hi:[1,0]
	v_pk_mul_f32 v[20:21], v[20:21], s[66:67] op_sel_hi:[1,0]
	v_pk_mul_f32 v[16:17], v[16:17], s[66:67] op_sel_hi:[1,0]
	v_pk_mul_f32 v[22:23], v[22:23], s[66:67] op_sel_hi:[1,0]
	v_lshl_add_u64 v[52:53], s[28:29], 0, v[12:13]
	v_pk_mul_f32 v[48:49], v[14:15], s[66:67] op_sel_hi:[1,0]
	v_pk_mul_f32 v[50:51], v[18:19], s[66:67] op_sel_hi:[1,0]
	v_cvt_pk_bf16_f32 v14, v16, v17
	v_cvt_pk_bf16_f32 v15, v20, v21
	v_cvt_pk_bf16_f32 v16, v24, v25
	v_cvt_pk_bf16_f32 v17, v26, v27
	v_cvt_pk_bf16_f32 v21, v22, v23
	v_lshl_add_u64 v[22:23], v[52:53], 0, v[2:3]
	v_cvt_pk_bf16_f32 v18, v46, v47
	v_cvt_pk_bf16_f32 v19, v48, v49
	v_cvt_pk_bf16_f32 v20, v50, v51
	global_store_dwordx4 v[22:23], v[14:17], off
	global_store_dwordx4 v[22:23], v[18:21], off offset:64
	global_load_dwordx4 v[14:17], v[10:11], off
	s_nop 0
	global_load_dwordx4 v[22:25], v[10:11], off offset:128
	global_load_dwordx4 v[46:49], v[10:11], off offset:16
	global_load_dwordx4 v[50:53], v[10:11], off offset:144
	s_waitcnt vmcnt(0) lgkmcnt(0)
	v_lshlrev_b32_e32 v18, 16, v28
	v_and_b32_e32 v19, 0xffff0000, v28
	v_lshlrev_b32_e32 v20, 16, v29
	v_and_b32_e32 v21, 0xffff0000, v29
	v_lshlrev_b32_e32 v26, 16, v30
	v_and_b32_e32 v27, 0xffff0000, v30
	v_lshlrev_b32_e32 v28, 16, v31
	v_and_b32_e32 v29, 0xffff0000, v31
	v_lshlrev_b32_e32 v30, 16, v42
	v_and_b32_e32 v31, 0xffff0000, v42
	v_lshlrev_b32_e32 v42, 16, v43
	v_and_b32_e32 v43, 0xffff0000, v43
	v_pk_mul_f32 v[60:61], v[30:31], v[30:31]
	v_pk_mul_f32 v[58:59], v[42:43], v[42:43]
	v_pk_fma_f32 v[60:61], v[18:19], v[18:19], v[60:61]
	v_lshlrev_b32_e32 v54, 16, v44
	v_and_b32_e32 v55, 0xffff0000, v44
	v_pk_fma_f32 v[58:59], v[20:21], v[20:21], v[58:59]
	v_add_f32_e32 v3, v60, v61
	v_pk_mul_f32 v[56:57], v[54:55], v[54:55]
	v_add_f32_e32 v3, v3, v58
	v_lshlrev_b32_e32 v44, 16, v45
	v_and_b32_e32 v45, 0xffff0000, v45
	v_pk_fma_f32 v[56:57], v[26:27], v[26:27], v[56:57]
	v_add_f32_e32 v3, v59, v3
	v_pk_mul_f32 v[62:63], v[44:45], v[44:45]
	v_add_f32_e32 v3, v56, v3
	v_pk_fma_f32 v[62:63], v[28:29], v[28:29], v[62:63]
	v_add_f32_e32 v3, v57, v3
	v_add_f32_e32 v3, v62, v3
	v_add_f32_e32 v3, v63, v3
	ds_bpermute_b32 v5, v39, v3
	s_waitcnt lgkmcnt(0)
	v_add_f32_e32 v3, v3, v5
	ds_bpermute_b32 v5, v40, v3
	s_waitcnt lgkmcnt(0)
	v_add_f32_e32 v3, v3, v5
	v_fmamk_f32 v3, v3, 0x3c800000, v206
	v_mul_f32_e32 v5, 0x4b800000, v3
	v_cmp_gt_f32_e32 vcc, s35, v3
	s_nop 1
	v_cndmask_b32_e32 v3, v3, v5, vcc
	v_rsq_f32_e32 v3, v3
	s_nop 0
	v_mul_f32_e32 v5, 0x45800000, v3
	v_cndmask_b32_e32 v56, v3, v5, vcc
	v_pk_mul_f32 v[18:19], v[56:57], v[18:19] op_sel_hi:[0,1]
	v_pk_mul_f32 v[30:31], v[56:57], v[30:31] op_sel_hi:[0,1]
	v_pk_mul_f32 v[20:21], v[56:57], v[20:21] op_sel_hi:[0,1]
	v_pk_mul_f32 v[42:43], v[56:57], v[42:43] op_sel_hi:[0,1]
	v_pk_mul_f32 v[26:27], v[56:57], v[26:27] op_sel_hi:[0,1]
	v_pk_mul_f32 v[54:55], v[56:57], v[54:55] op_sel_hi:[0,1]
	v_pk_mul_f32 v[28:29], v[56:57], v[28:29] op_sel_hi:[0,1]
	v_pk_mul_f32 v[44:45], v[56:57], v[44:45] op_sel_hi:[0,1]
	v_pk_mul_f32 v[18:19], v[14:15], v[18:19]
	v_pk_mul_f32 v[14:15], v[22:23], v[30:31]
	v_pk_mul_f32 v[22:23], v[16:17], v[20:21]
	v_pk_mul_f32 v[16:17], v[24:25], v[42:43]
	v_pk_mul_f32 v[26:27], v[46:47], v[26:27]
	v_pk_mul_f32 v[20:21], v[50:51], v[54:55]
	v_pk_mul_f32 v[28:29], v[48:49], v[28:29]
	v_pk_mul_f32 v[24:25], v[52:53], v[44:45]
	s_and_saveexec_b64 s[4:5], s[2:3]
	s_cbranch_execz .LBB0_629
	v_mov_b32_e32 v9, v1
	v_lshl_add_u64 v[30:31], v[8:9], 2, s[64:65]
	v_lshl_add_u64 v[42:43], s[24:25], 0, v[30:31]
	v_mov_b32_e32 v5, v1
	v_lshl_add_u64 v[50:51], v[42:43], 0, v[4:5]
	v_lshl_add_u64 v[30:31], s[26:27], 0, v[30:31]
	v_lshl_add_u64 v[30:31], v[30:31], 0, v[4:5]
	global_load_dwordx4 v[42:45], v[50:51], off
	global_load_dwordx4 v[46:49], v[30:31], off
	global_load_dwordx4 v[212:215], v[50:51], off offset:16
	global_load_dwordx4 v[216:219], v[30:31], off offset:16
	s_waitcnt vmcnt(0) lgkmcnt(0)
	v_pk_mul_f32 v[52:53], v[18:19], v[46:47]
	v_pk_mul_f32 v[46:47], v[14:15], v[46:47]
	v_pk_fma_f32 v[14:15], v[14:15], v[42:43], v[52:53]
	v_pk_fma_f32 v[18:19], v[18:19], v[42:43], v[46:47] neg_lo:[0,0,1] neg_hi:[0,0,1]
	v_pk_mul_f32 v[42:43], v[22:23], v[48:49]
	v_pk_mul_f32 v[46:47], v[16:17], v[48:49]
	v_pk_fma_f32 v[16:17], v[16:17], v[44:45], v[42:43]
	v_pk_fma_f32 v[22:23], v[22:23], v[44:45], v[46:47] neg_lo:[0,0,1] neg_hi:[0,0,1]
	v_pk_mul_f32 v[30:31], v[26:27], v[216:217]
	v_pk_mul_f32 v[216:217], v[20:21], v[216:217]
	v_pk_fma_f32 v[20:21], v[20:21], v[212:213], v[30:31]
	v_pk_fma_f32 v[26:27], v[26:27], v[212:213], v[216:217] neg_lo:[0,0,1] neg_hi:[0,0,1]
	v_pk_mul_f32 v[30:31], v[28:29], v[218:219]
	v_pk_mul_f32 v[212:213], v[24:25], v[218:219]
	v_pk_fma_f32 v[24:25], v[24:25], v[214:215], v[30:31]
	v_pk_fma_f32 v[28:29], v[28:29], v[214:215], v[212:213] neg_lo:[0,0,1] neg_hi:[0,0,1]
.LBB0_629:
	s_or_b64 exec, exec, s[4:5]
	v_lshl_add_u64 v[12:13], s[12:13], 0, v[12:13]
	v_mov_b32_e32 v3, v1
	v_pk_mul_f32 v[30:31], v[14:15], s[66:67] op_sel_hi:[1,0]
	v_lshl_add_u64 v[14:15], v[12:13], 0, v[2:3]
	s_mov_b32 s4, 0xa80000
	v_pk_mul_f32 v[28:29], v[28:29], s[66:67] op_sel_hi:[1,0]
	v_pk_mul_f32 v[26:27], v[26:27], s[66:67] op_sel_hi:[1,0]
	v_pk_mul_f32 v[22:23], v[22:23], s[66:67] op_sel_hi:[1,0]
	v_pk_mul_f32 v[18:19], v[18:19], s[66:67] op_sel_hi:[1,0]
	v_add_co_u32_e32 v14, vcc, s4, v14
	v_pk_mul_f32 v[24:25], v[24:25], s[66:67] op_sel_hi:[1,0]
	v_pk_mul_f32 v[42:43], v[16:17], s[66:67] op_sel_hi:[1,0]
	v_pk_mul_f32 v[20:21], v[20:21], s[66:67] op_sel_hi:[1,0]
	v_cvt_pk_bf16_f32 v16, v18, v19
	v_cvt_pk_bf16_f32 v17, v22, v23
	v_cvt_pk_bf16_f32 v18, v26, v27
	v_cvt_pk_bf16_f32 v19, v28, v29
	v_addc_co_u32_e32 v15, vcc, 0, v15, vcc
	global_store_dwordx4 v[14:15], v[16:19], off offset:128
	s_nop 1
	v_cvt_pk_bf16_f32 v16, v30, v31
	v_cvt_pk_bf16_f32 v17, v42, v43
	v_cvt_pk_bf16_f32 v18, v20, v21
	v_cvt_pk_bf16_f32 v19, v24, v25
	global_store_dwordx4 v[14:15], v[16:19], off offset:192
	global_load_dwordx4 v[16:19], v[6:7], off offset:1824
	s_nop 0
	global_load_dwordx4 v[20:23], v[6:7], off offset:1888
	global_load_dwordx4 v[24:27], v[10:11], off
	global_load_dwordx4 v[28:31], v[10:11], off offset:128
	global_load_dwordx4 v[42:45], v[10:11], off offset:16
	global_load_dwordx4 v[46:49], v[10:11], off offset:144
	s_waitcnt vmcnt(0) lgkmcnt(0)
	v_lshlrev_b32_e32 v50, 16, v16
	v_lshlrev_b32_e32 v54, 16, v20
	v_and_b32_e32 v55, 0xffff0000, v20
	v_and_b32_e32 v51, 0xffff0000, v16
	v_lshlrev_b32_e32 v20, 16, v21
	v_and_b32_e32 v21, 0xffff0000, v21
	v_pk_mul_f32 v[62:63], v[54:55], v[54:55]
	v_lshlrev_b32_e32 v16, 16, v17
	v_and_b32_e32 v17, 0xffff0000, v17
	v_pk_mul_f32 v[60:61], v[20:21], v[20:21]
	v_pk_fma_f32 v[62:63], v[50:51], v[50:51], v[62:63]
	v_lshlrev_b32_e32 v56, 16, v22
	v_and_b32_e32 v57, 0xffff0000, v22
	v_pk_fma_f32 v[60:61], v[16:17], v[16:17], v[60:61]
	v_add_f32_e32 v3, v62, v63
	v_lshlrev_b32_e32 v52, 16, v18
	v_and_b32_e32 v53, 0xffff0000, v18
	v_pk_mul_f32 v[58:59], v[56:57], v[56:57]
	v_add_f32_e32 v3, v3, v60
	v_lshlrev_b32_e32 v22, 16, v23
	v_and_b32_e32 v23, 0xffff0000, v23
	v_pk_fma_f32 v[58:59], v[52:53], v[52:53], v[58:59]
	v_add_f32_e32 v3, v61, v3
	v_lshlrev_b32_e32 v18, 16, v19
	v_and_b32_e32 v19, 0xffff0000, v19
	v_pk_mul_f32 v[64:65], v[22:23], v[22:23]
	v_add_f32_e32 v3, v58, v3
	v_pk_fma_f32 v[64:65], v[18:19], v[18:19], v[64:65]
	v_add_f32_e32 v3, v59, v3
	v_add_f32_e32 v3, v64, v3
	v_add_f32_e32 v3, v65, v3
	ds_bpermute_b32 v5, v39, v3
	s_waitcnt lgkmcnt(0)
	v_add_f32_e32 v3, v3, v5
	ds_bpermute_b32 v5, v40, v3
	s_waitcnt lgkmcnt(0)
	v_add_f32_e32 v3, v3, v5
	v_fmamk_f32 v3, v3, 0x3c800000, v206
	v_mul_f32_e32 v5, 0x4b800000, v3
	v_cmp_gt_f32_e32 vcc, s35, v3
	s_nop 1
	v_cndmask_b32_e32 v3, v3, v5, vcc
	v_rsq_f32_e32 v3, v3
	s_nop 0
	v_mul_f32_e32 v5, 0x45800000, v3
	v_cndmask_b32_e32 v58, v3, v5, vcc
	v_pk_mul_f32 v[50:51], v[58:59], v[50:51] op_sel_hi:[0,1]
	v_pk_mul_f32 v[54:55], v[58:59], v[54:55] op_sel_hi:[0,1]
	v_pk_mul_f32 v[60:61], v[58:59], v[16:17] op_sel_hi:[0,1]
	v_pk_mul_f32 v[62:63], v[58:59], v[20:21] op_sel_hi:[0,1]
	v_pk_mul_f32 v[52:53], v[58:59], v[52:53] op_sel_hi:[0,1]
	v_pk_mul_f32 v[56:57], v[58:59], v[56:57] op_sel_hi:[0,1]
	v_pk_mul_f32 v[64:65], v[58:59], v[18:19] op_sel_hi:[0,1]
	v_pk_mul_f32 v[58:59], v[58:59], v[22:23] op_sel_hi:[0,1]
	v_pk_mul_f32 v[20:21], v[24:25], v[50:51]
	v_pk_mul_f32 v[16:17], v[28:29], v[54:55]
	v_pk_mul_f32 v[24:25], v[26:27], v[60:61]
	v_pk_mul_f32 v[18:19], v[30:31], v[62:63]
	v_pk_mul_f32 v[28:29], v[42:43], v[52:53]
	v_pk_mul_f32 v[22:23], v[46:47], v[56:57]
	v_pk_mul_f32 v[30:31], v[44:45], v[64:65]
	v_pk_mul_f32 v[26:27], v[48:49], v[58:59]
	s_and_saveexec_b64 s[4:5], s[2:3]
	s_cbranch_execz .LBB0_631
	v_mov_b32_e32 v9, v1
	v_lshl_add_u64 v[42:43], v[8:9], 2, s[64:65]
	v_lshl_add_u64 v[44:45], s[24:25], 0, v[42:43]
	v_mov_b32_e32 v5, v1
	v_lshl_add_u64 v[50:51], v[44:45], 0, v[4:5]
	v_lshl_add_u64 v[42:43], s[26:27], 0, v[42:43]
	v_lshl_add_u64 v[52:53], v[42:43], 0, v[4:5]
	global_load_dwordx4 v[42:45], v[50:51], off
	global_load_dwordx4 v[46:49], v[52:53], off
	global_load_dwordx4 v[212:215], v[50:51], off offset:16
	global_load_dwordx4 v[216:219], v[52:53], off offset:16
	s_waitcnt vmcnt(0) lgkmcnt(0)
	v_pk_mul_f32 v[54:55], v[20:21], v[46:47]
	v_pk_mul_f32 v[46:47], v[16:17], v[46:47]
	v_pk_fma_f32 v[16:17], v[16:17], v[42:43], v[54:55]
	v_pk_fma_f32 v[20:21], v[20:21], v[42:43], v[46:47] neg_lo:[0,0,1] neg_hi:[0,0,1]
	v_pk_mul_f32 v[42:43], v[24:25], v[48:49]
	v_pk_mul_f32 v[46:47], v[18:19], v[48:49]
	v_pk_fma_f32 v[18:19], v[18:19], v[44:45], v[42:43]
	v_pk_fma_f32 v[24:25], v[24:25], v[44:45], v[46:47] neg_lo:[0,0,1] neg_hi:[0,0,1]
	v_pk_mul_f32 v[50:51], v[28:29], v[216:217]
	v_pk_mul_f32 v[216:217], v[22:23], v[216:217]
	v_pk_fma_f32 v[22:23], v[22:23], v[212:213], v[50:51]
	v_pk_fma_f32 v[28:29], v[28:29], v[212:213], v[216:217] neg_lo:[0,0,1] neg_hi:[0,0,1]
	v_pk_mul_f32 v[212:213], v[30:31], v[218:219]
	v_pk_mul_f32 v[216:217], v[26:27], v[218:219]
	v_pk_fma_f32 v[26:27], v[26:27], v[214:215], v[212:213]
	v_pk_fma_f32 v[30:31], v[30:31], v[214:215], v[216:217] neg_lo:[0,0,1] neg_hi:[0,0,1]
.LBB0_631:
	s_or_b64 exec, exec, s[4:5]
	v_pk_mul_f32 v[30:31], v[30:31], s[66:67] op_sel_hi:[1,0]
	v_pk_mul_f32 v[28:29], v[28:29], s[66:67] op_sel_hi:[1,0]
	v_pk_mul_f32 v[24:25], v[24:25], s[66:67] op_sel_hi:[1,0]
	v_pk_mul_f32 v[20:21], v[20:21], s[66:67] op_sel_hi:[1,0]
	v_pk_mul_f32 v[26:27], v[26:27], s[66:67] op_sel_hi:[1,0]
	v_pk_mul_f32 v[42:43], v[16:17], s[66:67] op_sel_hi:[1,0]
	v_pk_mul_f32 v[44:45], v[18:19], s[66:67] op_sel_hi:[1,0]
	v_pk_mul_f32 v[22:23], v[22:23], s[66:67] op_sel_hi:[1,0]
	v_cvt_pk_bf16_f32 v16, v20, v21
	v_cvt_pk_bf16_f32 v17, v24, v25
	v_cvt_pk_bf16_f32 v18, v28, v29
	v_cvt_pk_bf16_f32 v19, v30, v31
	global_store_dwordx4 v[14:15], v[16:19], off offset:256
	s_nop 1
	v_cvt_pk_bf16_f32 v16, v42, v43
	v_cvt_pk_bf16_f32 v17, v44, v45
	v_cvt_pk_bf16_f32 v18, v22, v23
	v_cvt_pk_bf16_f32 v19, v26, v27
	global_store_dwordx4 v[14:15], v[16:19], off offset:320
	global_load_dwordx4 v[14:17], v[6:7], off offset:1952
	s_nop 0
	global_load_dwordx4 v[18:21], v[6:7], off offset:2016
	global_load_dwordx4 v[22:25], v[10:11], off
	global_load_dwordx4 v[26:29], v[10:11], off offset:128
	global_load_dwordx4 v[42:45], v[10:11], off offset:16
	global_load_dwordx4 v[46:49], v[10:11], off offset:144
	s_waitcnt vmcnt(0) lgkmcnt(0)
	v_lshlrev_b32_e32 v10, 16, v14
	v_lshlrev_b32_e32 v50, 16, v18
	v_and_b32_e32 v51, 0xffff0000, v18
	v_and_b32_e32 v11, 0xffff0000, v14
	v_lshlrev_b32_e32 v18, 16, v19
	v_and_b32_e32 v19, 0xffff0000, v19
	v_pk_mul_f32 v[58:59], v[50:51], v[50:51]
	v_lshlrev_b32_e32 v14, 16, v15
	v_and_b32_e32 v15, 0xffff0000, v15
	v_pk_mul_f32 v[56:57], v[18:19], v[18:19]
	v_pk_fma_f32 v[58:59], v[10:11], v[10:11], v[58:59]
	v_lshlrev_b32_e32 v52, 16, v20
	v_and_b32_e32 v53, 0xffff0000, v20
	v_pk_fma_f32 v[56:57], v[14:15], v[14:15], v[56:57]
	v_add_f32_e32 v3, v58, v59
	v_lshlrev_b32_e32 v30, 16, v16
	v_and_b32_e32 v31, 0xffff0000, v16
	v_pk_mul_f32 v[54:55], v[52:53], v[52:53]
	v_add_f32_e32 v3, v3, v56
	v_lshlrev_b32_e32 v20, 16, v21
	v_and_b32_e32 v21, 0xffff0000, v21
	v_pk_fma_f32 v[54:55], v[30:31], v[30:31], v[54:55]
	v_add_f32_e32 v3, v57, v3
	v_lshlrev_b32_e32 v16, 16, v17
	v_and_b32_e32 v17, 0xffff0000, v17
	v_pk_mul_f32 v[60:61], v[20:21], v[20:21]
	v_add_f32_e32 v3, v54, v3
	v_pk_fma_f32 v[60:61], v[16:17], v[16:17], v[60:61]
	v_add_f32_e32 v3, v55, v3
	v_add_f32_e32 v3, v60, v3
	v_add_f32_e32 v3, v61, v3
	ds_bpermute_b32 v5, v39, v3
	s_waitcnt lgkmcnt(0)
	v_add_f32_e32 v3, v3, v5
	ds_bpermute_b32 v5, v40, v3
	s_waitcnt lgkmcnt(0)
	v_add_f32_e32 v3, v3, v5
	v_fmamk_f32 v3, v3, 0x3c800000, v206
	v_mul_f32_e32 v5, 0x4b800000, v3
	v_cmp_gt_f32_e32 vcc, s35, v3
	s_nop 1
	v_cndmask_b32_e32 v3, v3, v5, vcc
	v_rsq_f32_e32 v3, v3
	s_nop 0
	v_mul_f32_e32 v5, 0x45800000, v3
	v_cndmask_b32_e32 v54, v3, v5, vcc
	v_pk_mul_f32 v[10:11], v[54:55], v[10:11] op_sel_hi:[0,1]
	v_pk_mul_f32 v[50:51], v[54:55], v[50:51] op_sel_hi:[0,1]
	v_pk_mul_f32 v[14:15], v[54:55], v[14:15] op_sel_hi:[0,1]
	v_pk_mul_f32 v[18:19], v[54:55], v[18:19] op_sel_hi:[0,1]
	v_pk_mul_f32 v[30:31], v[54:55], v[30:31] op_sel_hi:[0,1]
	v_pk_mul_f32 v[52:53], v[54:55], v[52:53] op_sel_hi:[0,1]
	v_pk_mul_f32 v[56:57], v[54:55], v[16:17] op_sel_hi:[0,1]
	v_pk_mul_f32 v[54:55], v[54:55], v[20:21] op_sel_hi:[0,1]
	v_pk_mul_f32 v[16:17], v[22:23], v[10:11]
	v_pk_mul_f32 v[10:11], v[26:27], v[50:51]
	v_pk_mul_f32 v[20:21], v[24:25], v[14:15]
	v_pk_mul_f32 v[14:15], v[28:29], v[18:19]
	v_pk_mul_f32 v[24:25], v[42:43], v[30:31]
	v_pk_mul_f32 v[18:19], v[46:47], v[52:53]
	v_pk_mul_f32 v[26:27], v[44:45], v[56:57]
	v_pk_mul_f32 v[22:23], v[48:49], v[54:55]
	s_and_saveexec_b64 s[4:5], s[2:3]
	s_cbranch_execz .LBB0_633
	v_mov_b32_e32 v9, v1
	v_lshl_add_u64 v[28:29], v[8:9], 2, s[64:65]
	v_lshl_add_u64 v[30:31], s[24:25], 0, v[28:29]
	v_mov_b32_e32 v5, v1
	v_lshl_add_u64 v[46:47], v[30:31], 0, v[4:5]
	v_lshl_add_u64 v[28:29], s[26:27], 0, v[28:29]
	v_lshl_add_u64 v[48:49], v[28:29], 0, v[4:5]
	global_load_dwordx4 v[28:31], v[46:47], off
	global_load_dwordx4 v[42:45], v[48:49], off
	global_load_dwordx4 v[212:215], v[46:47], off offset:16
	global_load_dwordx4 v[216:219], v[48:49], off offset:16
	s_waitcnt vmcnt(0) lgkmcnt(0)
	v_pk_mul_f32 v[50:51], v[16:17], v[42:43]
	v_pk_mul_f32 v[42:43], v[10:11], v[42:43]
	v_pk_fma_f32 v[10:11], v[10:11], v[28:29], v[50:51]
	v_pk_fma_f32 v[16:17], v[16:17], v[28:29], v[42:43] neg_lo:[0,0,1] neg_hi:[0,0,1]
	v_pk_mul_f32 v[28:29], v[20:21], v[44:45]
	v_pk_mul_f32 v[42:43], v[14:15], v[44:45]
	v_pk_fma_f32 v[14:15], v[14:15], v[30:31], v[28:29]
	v_pk_fma_f32 v[20:21], v[20:21], v[30:31], v[42:43] neg_lo:[0,0,1] neg_hi:[0,0,1]
	v_pk_mul_f32 v[46:47], v[24:25], v[216:217]
	v_pk_mul_f32 v[216:217], v[18:19], v[216:217]
	v_pk_fma_f32 v[18:19], v[18:19], v[212:213], v[46:47]
	v_pk_fma_f32 v[24:25], v[24:25], v[212:213], v[216:217] neg_lo:[0,0,1] neg_hi:[0,0,1]
	v_pk_mul_f32 v[212:213], v[26:27], v[218:219]
	v_pk_mul_f32 v[216:217], v[22:23], v[218:219]
	v_pk_fma_f32 v[22:23], v[22:23], v[214:215], v[212:213]
	v_pk_fma_f32 v[26:27], v[26:27], v[214:215], v[216:217] neg_lo:[0,0,1] neg_hi:[0,0,1]
.LBB0_633:
	s_or_b64 exec, exec, s[4:5]
	v_mov_b32_e32 v3, v1
	v_pk_mul_f32 v[20:21], v[20:21], s[66:67] op_sel_hi:[1,0]
	v_lshl_add_u64 v[12:13], v[12:13], 0, v[2:3]
	s_mov_b32 s4, 0xa80000
	v_pk_mul_f32 v[26:27], v[26:27], s[66:67] op_sel_hi:[1,0]
	v_pk_mul_f32 v[24:25], v[24:25], s[66:67] op_sel_hi:[1,0]
	v_pk_mul_f32 v[16:17], v[16:17], s[66:67] op_sel_hi:[1,0]
	v_pk_mul_f32 v[22:23], v[22:23], s[66:67] op_sel_hi:[1,0]
	v_pk_mul_f32 v[10:11], v[10:11], s[66:67] op_sel_hi:[1,0]
	v_pk_mul_f32 v[28:29], v[14:15], s[66:67] op_sel_hi:[1,0]
	v_pk_mul_f32 v[18:19], v[18:19], s[66:67] op_sel_hi:[1,0]
	v_cvt_pk_bf16_f32 v15, v20, v21
	v_add_co_u32_e32 v20, vcc, s4, v12
	v_cvt_pk_bf16_f32 v14, v16, v17
	v_cvt_pk_bf16_f32 v16, v24, v25
	v_cvt_pk_bf16_f32 v17, v26, v27
	v_addc_co_u32_e32 v21, vcc, 0, v13, vcc
	v_cvt_pk_bf16_f32 v10, v10, v11
	v_cvt_pk_bf16_f32 v11, v28, v29
	v_cvt_pk_bf16_f32 v12, v18, v19
	v_cvt_pk_bf16_f32 v13, v22, v23
	global_store_dwordx4 v[20:21], v[14:17], off offset:384
	global_store_dwordx4 v[20:21], v[10:13], off offset:448
	global_load_dwordx4 v[12:15], v[6:7], off offset:2080
	s_nop 0
	global_load_dwordx4 v[16:19], v[6:7], off offset:2144
	v_mov_b32_e32 v5, v1
	v_lshl_add_u64 v[10:11], s[30:31], 0, v[4:5]
	global_load_dwordx4 v[22:25], v[10:11], off
	global_load_dwordx4 v[26:29], v[10:11], off offset:128
	global_load_dwordx4 v[42:45], v[10:11], off offset:16
	global_load_dwordx4 v[46:49], v[10:11], off offset:144
	s_waitcnt vmcnt(0) lgkmcnt(0)
	v_lshlrev_b32_e32 v20, 16, v12
	v_lshlrev_b32_e32 v50, 16, v16
	v_and_b32_e32 v51, 0xffff0000, v16
	v_and_b32_e32 v21, 0xffff0000, v12
	v_lshlrev_b32_e32 v16, 16, v17
	v_and_b32_e32 v17, 0xffff0000, v17
	v_pk_mul_f32 v[58:59], v[50:51], v[50:51]
	v_lshlrev_b32_e32 v12, 16, v13
	v_and_b32_e32 v13, 0xffff0000, v13
	v_pk_mul_f32 v[56:57], v[16:17], v[16:17]
	v_pk_fma_f32 v[58:59], v[20:21], v[20:21], v[58:59]
	v_lshlrev_b32_e32 v52, 16, v18
	v_and_b32_e32 v53, 0xffff0000, v18
	v_pk_fma_f32 v[56:57], v[12:13], v[12:13], v[56:57]
	v_add_f32_e32 v9, v58, v59
	v_lshlrev_b32_e32 v30, 16, v14
	v_and_b32_e32 v31, 0xffff0000, v14
	v_pk_mul_f32 v[54:55], v[52:53], v[52:53]
	v_add_f32_e32 v9, v9, v56
	v_lshlrev_b32_e32 v18, 16, v19
	v_and_b32_e32 v19, 0xffff0000, v19
	v_pk_fma_f32 v[54:55], v[30:31], v[30:31], v[54:55]
	v_add_f32_e32 v9, v57, v9
	v_lshlrev_b32_e32 v14, 16, v15
	v_and_b32_e32 v15, 0xffff0000, v15
	v_pk_mul_f32 v[60:61], v[18:19], v[18:19]
	v_add_f32_e32 v9, v54, v9
	v_pk_fma_f32 v[60:61], v[14:15], v[14:15], v[60:61]
	v_add_f32_e32 v9, v55, v9
	v_add_f32_e32 v9, v60, v9
	v_add_f32_e32 v9, v61, v9
	ds_bpermute_b32 v54, v39, v9
	s_waitcnt lgkmcnt(0)
	v_add_f32_e32 v9, v9, v54
	ds_bpermute_b32 v54, v40, v9
	s_waitcnt lgkmcnt(0)
	v_add_f32_e32 v9, v9, v54
	v_fmamk_f32 v9, v9, 0x3c800000, v206
	v_mul_f32_e32 v54, 0x4b800000, v9
	v_cmp_gt_f32_e32 vcc, s35, v9
	s_nop 1
	v_cndmask_b32_e32 v9, v9, v54, vcc
	v_rsq_f32_e32 v9, v9
	s_nop 0
	v_mul_f32_e32 v54, 0x45800000, v9
	v_cndmask_b32_e32 v54, v9, v54, vcc
	v_pk_mul_f32 v[20:21], v[54:55], v[20:21] op_sel_hi:[0,1]
	v_pk_mul_f32 v[50:51], v[54:55], v[50:51] op_sel_hi:[0,1]
	v_pk_mul_f32 v[12:13], v[54:55], v[12:13] op_sel_hi:[0,1]
	v_pk_mul_f32 v[16:17], v[54:55], v[16:17] op_sel_hi:[0,1]
	v_pk_mul_f32 v[30:31], v[54:55], v[30:31] op_sel_hi:[0,1]
	v_pk_mul_f32 v[52:53], v[54:55], v[52:53] op_sel_hi:[0,1]
	v_pk_mul_f32 v[56:57], v[54:55], v[14:15] op_sel_hi:[0,1]
	v_pk_mul_f32 v[54:55], v[54:55], v[18:19] op_sel_hi:[0,1]
	v_pk_mul_f32 v[22:23], v[22:23], v[20:21]
	v_pk_mul_f32 v[14:15], v[26:27], v[50:51]
	v_pk_mul_f32 v[24:25], v[24:25], v[12:13]
	v_pk_mul_f32 v[16:17], v[28:29], v[16:17]
	v_pk_mul_f32 v[26:27], v[42:43], v[30:31]
	v_pk_mul_f32 v[18:19], v[46:47], v[52:53]
	v_pk_mul_f32 v[28:29], v[44:45], v[56:57]
	v_pk_mul_f32 v[20:21], v[48:49], v[54:55]
	s_and_saveexec_b64 s[4:5], s[2:3]
	s_cbranch_execz .LBB0_635
	v_mov_b32_e32 v9, v1
	v_lshl_add_u64 v[12:13], v[8:9], 2, s[64:65]
	v_lshl_add_u64 v[30:31], s[24:25], 0, v[12:13]
	v_lshl_add_u64 v[30:31], v[30:31], 0, v[4:5]
	v_lshl_add_u64 v[12:13], s[26:27], 0, v[12:13]
	v_lshl_add_u64 v[12:13], v[12:13], 0, v[4:5]
	global_load_dwordx4 v[42:45], v[30:31], off
	global_load_dwordx4 v[46:49], v[12:13], off
	global_load_dwordx4 v[212:215], v[30:31], off offset:16
	global_load_dwordx4 v[216:219], v[12:13], off offset:16
	s_waitcnt vmcnt(0) lgkmcnt(0)
	v_pk_mul_f32 v[50:51], v[22:23], v[46:47]
	v_pk_mul_f32 v[46:47], v[14:15], v[46:47]
	v_pk_fma_f32 v[14:15], v[14:15], v[42:43], v[50:51]
	v_pk_fma_f32 v[22:23], v[22:23], v[42:43], v[46:47] neg_lo:[0,0,1] neg_hi:[0,0,1]
	v_pk_mul_f32 v[42:43], v[24:25], v[48:49]
	v_pk_mul_f32 v[46:47], v[16:17], v[48:49]
	v_pk_fma_f32 v[16:17], v[16:17], v[44:45], v[42:43]
	v_pk_fma_f32 v[24:25], v[24:25], v[44:45], v[46:47] neg_lo:[0,0,1] neg_hi:[0,0,1]
	v_pk_mul_f32 v[12:13], v[26:27], v[216:217]
	v_pk_mul_f32 v[30:31], v[18:19], v[216:217]
	v_pk_fma_f32 v[18:19], v[18:19], v[212:213], v[12:13]
	v_pk_fma_f32 v[26:27], v[26:27], v[212:213], v[30:31] neg_lo:[0,0,1] neg_hi:[0,0,1]
	v_pk_mul_f32 v[12:13], v[28:29], v[218:219]
	v_pk_mul_f32 v[30:31], v[20:21], v[218:219]
	v_pk_fma_f32 v[20:21], v[20:21], v[214:215], v[12:13]
	v_pk_fma_f32 v[28:29], v[28:29], v[214:215], v[30:31] neg_lo:[0,0,1] neg_hi:[0,0,1]
.LBB0_635:
	s_or_b64 exec, exec, s[4:5]
	v_lshlrev_b64 v[12:13], 8, v[0:1]
	v_lshl_add_u64 v[12:13], s[12:13], 0, v[12:13]
	v_cvt_pk_bf16_f32 v22, v22, v23
	v_cvt_pk_bf16_f32 v23, v24, v25
	v_cvt_pk_bf16_f32 v24, v26, v27
	v_lshl_add_u64 v[26:27], v[12:13], 0, v[2:3]
	s_mov_b32 s4, 0x2c80000
	v_add_co_u32_e32 v26, vcc, s4, v26
	v_cvt_pk_bf16_f32 v25, v28, v29
	s_nop 0
	v_addc_co_u32_e32 v27, vcc, 0, v27, vcc
	v_cvt_pk_bf16_f32 v14, v14, v15
	v_cvt_pk_bf16_f32 v15, v16, v17
	v_cvt_pk_bf16_f32 v16, v18, v19
	v_cvt_pk_bf16_f32 v17, v20, v21
	global_store_dwordx4 v[26:27], v[22:25], off
	global_store_dwordx4 v[26:27], v[14:17], off offset:64
	global_load_dwordx4 v[14:17], v[6:7], off offset:2208
	s_nop 0
	global_load_dwordx4 v[18:21], v[6:7], off offset:2272
	global_load_dwordx4 v[22:25], v[10:11], off
	global_load_dwordx4 v[26:29], v[10:11], off offset:128
	global_load_dwordx4 v[42:45], v[10:11], off offset:16
	global_load_dwordx4 v[46:49], v[10:11], off offset:144
	s_waitcnt vmcnt(0) lgkmcnt(0)
	v_lshlrev_b32_e32 v6, 16, v14
	v_lshlrev_b32_e32 v30, 16, v18
	v_and_b32_e32 v31, 0xffff0000, v18
	v_and_b32_e32 v7, 0xffff0000, v14
	v_lshlrev_b32_e32 v18, 16, v19
	v_and_b32_e32 v19, 0xffff0000, v19
	v_pk_mul_f32 v[56:57], v[30:31], v[30:31]
	v_lshlrev_b32_e32 v10, 16, v15
	v_and_b32_e32 v11, 0xffff0000, v15
	v_pk_mul_f32 v[54:55], v[18:19], v[18:19]
	v_pk_fma_f32 v[56:57], v[6:7], v[6:7], v[56:57]
	v_lshlrev_b32_e32 v50, 16, v20
	v_and_b32_e32 v51, 0xffff0000, v20
	v_pk_fma_f32 v[54:55], v[10:11], v[10:11], v[54:55]
	v_add_f32_e32 v0, v56, v57
	v_lshlrev_b32_e32 v14, 16, v16
	v_and_b32_e32 v15, 0xffff0000, v16
	v_pk_mul_f32 v[52:53], v[50:51], v[50:51]
	v_add_f32_e32 v0, v0, v54
	v_lshlrev_b32_e32 v20, 16, v21
	v_and_b32_e32 v21, 0xffff0000, v21
	v_pk_fma_f32 v[52:53], v[14:15], v[14:15], v[52:53]
	v_add_f32_e32 v0, v55, v0
	v_lshlrev_b32_e32 v16, 16, v17
	v_and_b32_e32 v17, 0xffff0000, v17
	v_pk_mul_f32 v[58:59], v[20:21], v[20:21]
	v_add_f32_e32 v0, v52, v0
	v_pk_fma_f32 v[58:59], v[16:17], v[16:17], v[58:59]
	v_add_f32_e32 v0, v53, v0
	v_add_f32_e32 v0, v58, v0
	v_add_f32_e32 v0, v59, v0
	ds_bpermute_b32 v3, v39, v0
	s_waitcnt lgkmcnt(0)
	v_add_f32_e32 v0, v0, v3
	ds_bpermute_b32 v3, v40, v0
	s_waitcnt lgkmcnt(0)
	v_add_f32_e32 v0, v0, v3
	v_fmamk_f32 v0, v0, 0x3c800000, v206
	v_mul_f32_e32 v3, 0x4b800000, v0
	v_cmp_gt_f32_e32 vcc, s35, v0
	s_nop 1
	v_cndmask_b32_e32 v0, v0, v3, vcc
	v_rsq_f32_e32 v0, v0
	s_nop 0
	v_mul_f32_e32 v3, 0x45800000, v0
	v_cndmask_b32_e32 v0, v0, v3, vcc
	v_pk_mul_f32 v[6:7], v[0:1], v[6:7] op_sel_hi:[0,1]
	v_pk_mul_f32 v[30:31], v[0:1], v[30:31] op_sel_hi:[0,1]
	v_pk_mul_f32 v[52:53], v[0:1], v[10:11] op_sel_hi:[0,1]
	v_pk_mul_f32 v[18:19], v[0:1], v[18:19] op_sel_hi:[0,1]
	v_pk_mul_f32 v[54:55], v[0:1], v[14:15] op_sel_hi:[0,1]
	v_pk_mul_f32 v[50:51], v[0:1], v[50:51] op_sel_hi:[0,1]
	v_pk_mul_f32 v[56:57], v[0:1], v[16:17] op_sel_hi:[0,1]
	v_pk_mul_f32 v[58:59], v[0:1], v[20:21] op_sel_hi:[0,1]
	v_pk_mul_f32 v[6:7], v[22:23], v[6:7]
	v_pk_mul_f32 v[10:11], v[26:27], v[30:31]
	v_pk_mul_f32 v[20:21], v[24:25], v[52:53]
	v_pk_mul_f32 v[14:15], v[28:29], v[18:19]
	v_pk_mul_f32 v[22:23], v[42:43], v[54:55]
	v_pk_mul_f32 v[16:17], v[46:47], v[50:51]
	v_pk_mul_f32 v[24:25], v[44:45], v[56:57]
	v_pk_mul_f32 v[18:19], v[48:49], v[58:59]
	s_and_saveexec_b64 s[4:5], s[2:3]
	s_cbranch_execz .LBB0_637
	v_mov_b32_e32 v9, v1
	v_lshl_add_u64 v[8:9], v[8:9], 2, s[64:65]
	v_lshl_add_u64 v[26:27], s[24:25], 0, v[8:9]
	v_mov_b32_e32 v5, v1
	v_lshl_add_u64 v[30:31], v[26:27], 0, v[4:5]
	v_lshl_add_u64 v[8:9], s[26:27], 0, v[8:9]
	v_lshl_add_u64 v[8:9], v[8:9], 0, v[4:5]
	global_load_dwordx4 v[26:29], v[30:31], off
	global_load_dwordx4 v[42:45], v[8:9], off
	global_load_dwordx4 v[212:215], v[30:31], off offset:16
	global_load_dwordx4 v[216:219], v[8:9], off offset:16
	s_waitcnt vmcnt(0) lgkmcnt(0)
	v_pk_mul_f32 v[46:47], v[6:7], v[42:43]
	v_pk_mul_f32 v[42:43], v[10:11], v[42:43]
	v_pk_fma_f32 v[10:11], v[10:11], v[26:27], v[46:47]
	v_pk_fma_f32 v[6:7], v[6:7], v[26:27], v[42:43] neg_lo:[0,0,1] neg_hi:[0,0,1]
	v_pk_mul_f32 v[26:27], v[20:21], v[44:45]
	v_pk_mul_f32 v[42:43], v[14:15], v[44:45]
	v_pk_fma_f32 v[14:15], v[14:15], v[28:29], v[26:27]
	v_pk_fma_f32 v[20:21], v[20:21], v[28:29], v[42:43] neg_lo:[0,0,1] neg_hi:[0,0,1]
	v_pk_mul_f32 v[8:9], v[22:23], v[216:217]
	v_pk_mul_f32 v[30:31], v[16:17], v[216:217]
	v_pk_fma_f32 v[16:17], v[16:17], v[212:213], v[8:9]
	v_pk_fma_f32 v[22:23], v[22:23], v[212:213], v[30:31] neg_lo:[0,0,1] neg_hi:[0,0,1]
	v_pk_mul_f32 v[8:9], v[24:25], v[218:219]
	v_pk_mul_f32 v[212:213], v[18:19], v[218:219]
	v_pk_fma_f32 v[18:19], v[18:19], v[214:215], v[8:9]
	v_pk_fma_f32 v[24:25], v[24:25], v[214:215], v[212:213] neg_lo:[0,0,1] neg_hi:[0,0,1]

.LBB0_639:
	s_mov_b32 s4, 0xaaaaaaab
	v_mul_hi_u32 v0, v41, s4
	v_lshrrev_b32_e32 v0, 8, v0
	v_mul_u32_u24_e32 v0, 0x180, v0
	v_sub_u32_e32 v29, v41, v0
	v_and_b32_e32 v28, 63, v29
	v_and_b32_e32 v0, 0x1c0, v29
	v_or_b32_e32 v3, v28, v36
	v_mov_b64_e32 v[12:13], s[20:21]
	v_mad_u64_u32 v[12:13], s[4:5], v3, s83, v[12:13]
	v_lshlrev_b32_e32 v0, 1, v0
	v_lshl_add_u64 v[12:13], v[12:13], 0, v[0:1]
	v_lshl_add_u64 v[16:17], v[12:13], 0, v[6:7]
	global_load_dwordx4 v[12:15], v[16:17], off offset:2592
	global_load_dwordx4 v[42:45], v[16:17], off offset:2656
	v_cmp_lt_u32_e64 s[4:5], s49, v29
	v_cmp_gt_u32_e32 vcc, s47, v29
	v_mov_b32_e32 v29, s10
	v_mov_b32_e32 v30, s8
	v_cndmask_b32_e32 v31, v29, v30, vcc
	v_mov_b32_e32 v29, s9
	v_mov_b32_e32 v30, s37
	v_cndmask_b32_e32 v30, v29, v30, vcc
	v_lshl_add_u64 v[30:31], s[18:19], 2, v[30:31]
	v_lshl_add_u64 v[30:31], v[30:31], 0, v[4:5]
	s_waitcnt vmcnt(0) lgkmcnt(0)
	v_lshlrev_b32_e32 v24, 16, v12
	v_and_b32_e32 v25, 0xffff0000, v12
	v_lshlrev_b32_e32 v20, 16, v13
	v_and_b32_e32 v21, 0xffff0000, v13
	v_lshlrev_b32_e32 v16, 16, v14
	v_and_b32_e32 v17, 0xffff0000, v14
	v_lshlrev_b32_e32 v12, 16, v15
	v_and_b32_e32 v13, 0xffff0000, v15
	v_lshlrev_b32_e32 v14, 16, v45
	v_and_b32_e32 v15, 0xffff0000, v45
	v_lshlrev_b32_e32 v26, 16, v42
	v_and_b32_e32 v27, 0xffff0000, v42
	v_lshlrev_b32_e32 v22, 16, v43
	v_and_b32_e32 v23, 0xffff0000, v43
	v_lshlrev_b32_e32 v18, 16, v44
	v_and_b32_e32 v19, 0xffff0000, v44
	v_pk_mul_f32 v[42:43], v[14:15], v[14:15]
	v_pk_mul_f32 v[50:51], v[22:23], v[22:23]
	v_pk_fma_f32 v[58:59], v[12:13], v[12:13], v[42:43]
	v_pk_mul_f32 v[42:43], v[18:19], v[18:19]
	v_pk_fma_f32 v[62:63], v[20:21], v[20:21], v[50:51]
	v_pk_fma_f32 v[60:61], v[16:17], v[16:17], v[42:43]
	global_load_dwordx4 v[42:45], v[30:31], off offset:16
	global_load_dwordx4 v[46:49], v[30:31], off offset:144
	global_load_dwordx4 v[50:53], v[30:31], off
	global_load_dwordx4 v[54:57], v[30:31], off offset:128
	v_pk_mul_f32 v[30:31], v[26:27], v[26:27]
	s_nop 0
	v_pk_fma_f32 v[30:31], v[24:25], v[24:25], v[30:31]
	s_nop 0
	v_add_f32_e32 v29, v30, v31
	v_add_f32_e32 v29, v29, v62
	v_add_f32_e32 v29, v63, v29
	v_add_f32_e32 v29, v60, v29
	v_add_f32_e32 v29, v61, v29
	v_add_f32_e32 v29, v58, v29
	v_add_f32_e32 v29, v59, v29
	ds_bpermute_b32 v30, v39, v29
	s_waitcnt lgkmcnt(0)
	v_add_f32_e32 v29, v29, v30
	ds_bpermute_b32 v30, v40, v29
	s_waitcnt lgkmcnt(0)
	v_add_f32_e32 v29, v29, v30
	v_fmamk_f32 v29, v29, 0x3c800000, v206
	v_cmp_gt_f32_e64 s[6:7], s35, v29
	v_mul_f32_e32 v30, 0x4b800000, v29
	s_nop 0
	v_cndmask_b32_e64 v29, v29, v30, s[6:7]
	v_rsq_f32_e32 v29, v29
	s_nop 0
	v_mul_f32_e32 v30, 0x45800000, v29
	v_cndmask_b32_e64 v30, v29, v30, s[6:7]
	v_pk_mul_f32 v[24:25], v[30:31], v[24:25] op_sel_hi:[0,1]
	v_pk_mul_f32 v[58:59], v[30:31], v[26:27] op_sel_hi:[0,1]
	v_pk_mul_f32 v[20:21], v[30:31], v[20:21] op_sel_hi:[0,1]
	v_pk_mul_f32 v[16:17], v[30:31], v[16:17] op_sel_hi:[0,1]
	v_pk_mul_f32 v[12:13], v[30:31], v[12:13] op_sel_hi:[0,1]
	s_waitcnt vmcnt(0)
	v_pk_mul_f32 v[26:27], v[50:51], v[24:25]
	v_pk_mul_f32 v[50:51], v[30:31], v[22:23] op_sel_hi:[0,1]
	v_pk_mul_f32 v[22:23], v[52:53], v[20:21]
	v_pk_mul_f32 v[20:21], v[56:57], v[50:51]
	v_pk_mul_f32 v[50:51], v[30:31], v[18:19] op_sel_hi:[0,1]
	v_pk_mul_f32 v[30:31], v[30:31], v[14:15] op_sel_hi:[0,1]
	v_pk_mul_f32 v[24:25], v[54:55], v[58:59]
	v_pk_mul_f32 v[18:19], v[42:43], v[16:17]
	v_pk_mul_f32 v[16:17], v[46:47], v[50:51]
	v_pk_mul_f32 v[14:15], v[44:45], v[12:13]
	v_pk_mul_f32 v[12:13], v[48:49], v[30:31]
	s_and_saveexec_b64 s[6:7], s[2:3]
	s_cbranch_execz .LBB0_641
	v_or_b32_e32 v28, v28, v34
	v_lshlrev_b32_e32 v28, 5, v28
	v_mov_b32_e32 v29, v1
	v_lshl_add_u64 v[28:29], v[28:29], 2, s[64:65]
	v_lshl_add_u64 v[46:47], v[8:9], 0, v[28:29]
	v_lshl_add_u64 v[48:49], v[10:11], 0, v[28:29]
	global_load_dwordx4 v[28:31], v[46:47], off
	global_load_dwordx4 v[42:45], v[48:49], off
	global_load_dwordx4 v[212:215], v[46:47], off offset:16
	global_load_dwordx4 v[216:219], v[48:49], off offset:16
	s_waitcnt vmcnt(0) lgkmcnt(0)
	v_pk_mul_f32 v[50:51], v[24:25], v[42:43]
	s_nop 0
	v_pk_fma_f32 v[50:51], v[26:27], v[28:29], v[50:51] neg_lo:[0,0,1] neg_hi:[0,0,1]
	v_pk_mul_f32 v[26:27], v[26:27], v[42:43]
	s_nop 0
	v_pk_fma_f32 v[24:25], v[24:25], v[28:29], v[26:27]
	v_pk_mul_f32 v[26:27], v[20:21], v[44:45]
	s_nop 0
	v_pk_fma_f32 v[52:53], v[22:23], v[30:31], v[26:27] neg_lo:[0,0,1] neg_hi:[0,0,1]
	v_pk_mul_f32 v[22:23], v[22:23], v[44:45]
	v_pk_fma_f32 v[20:21], v[20:21], v[30:31], v[22:23]
	v_pk_mul_f32 v[22:23], v[16:17], v[216:217]
	s_nop 0
	v_pk_fma_f32 v[22:23], v[18:19], v[212:213], v[22:23] neg_lo:[0,0,1] neg_hi:[0,0,1]
	v_pk_mul_f32 v[18:19], v[18:19], v[216:217]
	s_nop 0
	v_pk_fma_f32 v[16:17], v[16:17], v[212:213], v[18:19]
	v_pk_mul_f32 v[18:19], v[12:13], v[218:219]
	v_mov_b64_e32 v[26:27], v[50:51]
	v_pk_fma_f32 v[18:19], v[14:15], v[214:215], v[18:19] neg_lo:[0,0,1] neg_hi:[0,0,1]
	v_pk_mul_f32 v[14:15], v[14:15], v[218:219]
	s_nop 0
	v_pk_fma_f32 v[12:13], v[12:13], v[214:215], v[14:15]
	v_mov_b64_e32 v[14:15], v[18:19]
	v_mov_b64_e32 v[18:19], v[22:23]
	v_mov_b64_e32 v[22:23], v[52:53]
